# v20: v18 + deeper V-fragment ring in the diff-attn P.V block using the loops' free VGPR quads (8 quads in the pass-2 loops, 4 in pass-1)
# baseline (speedup 1.0000x reference)
.LBB0_44:
.LBB0_45:
	v_add3_u32 v190, s26, v178, v177
	ds_read_b64_tr_b16 v[240:241], v190 offset:9216
	ds_read_b64_tr_b16 v[242:243], v190 offset:11776
	ds_read_b64_tr_b16 v[244:245], v190 offset:9280
	ds_read_b64_tr_b16 v[246:247], v190 offset:11840
	ds_read_b64_tr_b16 v[214:215], v190 offset:9344
	ds_read_b64_tr_b16 v[216:217], v190 offset:11904
	ds_read_b64_tr_b16 v[166:167], v190 offset:9408
	ds_read_b64_tr_b16 v[168:169], v190 offset:11968
	v_exp_f32_e32 v82, v82
	v_exp_f32_e32 v83, v83
	v_exp_f32_e32 v84, v84
	v_exp_f32_e32 v85, v85
	v_exp_f32_e32 v86, v86
	v_exp_f32_e32 v87, v87
	v_exp_f32_e32 v88, v88
	v_exp_f32_e32 v89, v89
	v_add_f32_e32 v238, v82, v83
	v_add_f32_e32 v239, v239, v84
	v_add_f32_e32 v238, v238, v85
	v_cvt_pk_bf16_f32 v82, v82, v83
	v_cvt_pk_bf16_f32 v83, v84, v85
	v_cvt_pk_bf16_f32 v84, v86, v87
	v_cvt_pk_bf16_f32 v85, v88, v89
	s_setprio 1
	s_waitcnt lgkmcnt(6)
	v_mfma_f32_32x32x16_bf16 v[2:17], v[82:85], v[240:243], v[2:17]
	v_add_f32_e32 v239, v239, v86
	v_add_f32_e32 v238, v238, v87
	v_add_f32_e32 v239, v239, v88
	v_add_f32_e32 v238, v238, v89
	v_exp_f32_e32 v90, v90
	v_exp_f32_e32 v91, v91
	ds_read_b64_tr_b16 v[240:241], v190 offset:14336
	ds_read_b64_tr_b16 v[242:243], v190 offset:16896
	s_waitcnt lgkmcnt(6)
	v_mfma_f32_32x32x16_bf16 v[50:65], v[82:85], v[244:247], v[50:65]
	v_exp_f32_e32 v92, v92
	v_exp_f32_e32 v93, v93
	v_exp_f32_e32 v94, v94
	ds_read_b64_tr_b16 v[244:245], v190 offset:14400
	ds_read_b64_tr_b16 v[246:247], v190 offset:16960
	s_waitcnt lgkmcnt(6)
	v_mfma_f32_32x32x16_bf16 v[34:49], v[82:85], v[214:217], v[34:49]
	v_exp_f32_e32 v95, v95
	v_exp_f32_e32 v96, v96
	v_exp_f32_e32 v97, v97
	v_add_f32_e32 v239, v239, v90
	ds_read_b64_tr_b16 v[214:215], v190 offset:14464
	ds_read_b64_tr_b16 v[216:217], v190 offset:17024
	s_waitcnt lgkmcnt(6)
	v_mfma_f32_32x32x16_bf16 v[18:33], v[82:85], v[166:169], v[18:33]
	v_add_f32_e32 v238, v238, v91
	v_add_f32_e32 v239, v239, v92
	v_add_f32_e32 v238, v238, v93
	v_cvt_pk_bf16_f32 v90, v90, v91
	v_cvt_pk_bf16_f32 v91, v92, v93
	v_cvt_pk_bf16_f32 v92, v94, v95
	v_cvt_pk_bf16_f32 v93, v96, v97
	s_nop 0
	ds_read_b64_tr_b16 v[166:167], v190 offset:14528
	ds_read_b64_tr_b16 v[168:169], v190 offset:17088
	s_waitcnt lgkmcnt(6)
	v_mfma_f32_32x32x16_bf16 v[2:17], v[90:93], v[240:243], v[2:17]
	v_add_f32_e32 v239, v239, v94
	v_add_f32_e32 v238, v238, v95
	v_add_f32_e32 v239, v239, v96
	v_add_f32_e32 v238, v238, v97
	v_exp_f32_e32 v98, v98
	v_exp_f32_e32 v99, v99
	ds_read_b64_tr_b16 v[240:241], v190 offset:19456
	ds_read_b64_tr_b16 v[242:243], v190 offset:22016
	s_waitcnt lgkmcnt(6)
	v_mfma_f32_32x32x16_bf16 v[50:65], v[90:93], v[244:247], v[50:65]
	v_exp_f32_e32 v100, v100
	v_exp_f32_e32 v101, v101
	v_exp_f32_e32 v102, v102
	ds_read_b64_tr_b16 v[244:245], v190 offset:19520
	ds_read_b64_tr_b16 v[246:247], v190 offset:22080
	s_waitcnt lgkmcnt(6)
	v_mfma_f32_32x32x16_bf16 v[34:49], v[90:93], v[214:217], v[34:49]
	v_exp_f32_e32 v103, v103
	v_exp_f32_e32 v104, v104
	v_exp_f32_e32 v105, v105
	v_add_f32_e32 v239, v239, v98
	ds_read_b64_tr_b16 v[214:215], v190 offset:19584
	ds_read_b64_tr_b16 v[216:217], v190 offset:22144
	s_waitcnt lgkmcnt(6)
	v_mfma_f32_32x32x16_bf16 v[18:33], v[90:93], v[166:169], v[18:33]
	v_add_f32_e32 v238, v238, v99
	v_add_f32_e32 v239, v239, v100
	v_add_f32_e32 v238, v238, v101
	v_cvt_pk_bf16_f32 v98, v98, v99
	v_cvt_pk_bf16_f32 v99, v100, v101
	v_cvt_pk_bf16_f32 v100, v102, v103
	v_cvt_pk_bf16_f32 v101, v104, v105
	s_nop 0
	ds_read_b64_tr_b16 v[166:167], v190 offset:19648
	ds_read_b64_tr_b16 v[168:169], v190 offset:22208
	s_waitcnt lgkmcnt(6)
	v_mfma_f32_32x32x16_bf16 v[2:17], v[98:101], v[240:243], v[2:17]
	v_add_f32_e32 v239, v239, v102
	v_add_f32_e32 v238, v238, v103
	v_add_f32_e32 v239, v239, v104
	v_add_f32_e32 v238, v238, v105
	v_exp_f32_e32 v106, v106
	v_exp_f32_e32 v107, v107
	ds_read_b64_tr_b16 v[240:241], v190 offset:24576
	ds_read_b64_tr_b16 v[242:243], v190 offset:27136
	s_waitcnt lgkmcnt(6)
	v_mfma_f32_32x32x16_bf16 v[50:65], v[98:101], v[244:247], v[50:65]
	v_exp_f32_e32 v108, v108
	v_exp_f32_e32 v109, v109
	v_exp_f32_e32 v110, v110
	ds_read_b64_tr_b16 v[244:245], v190 offset:24640
	ds_read_b64_tr_b16 v[246:247], v190 offset:27200
	s_waitcnt lgkmcnt(6)
	v_mfma_f32_32x32x16_bf16 v[34:49], v[98:101], v[214:217], v[34:49]
	v_exp_f32_e32 v111, v111
	v_exp_f32_e32 v112, v112
	v_exp_f32_e32 v113, v113
	v_add_f32_e32 v239, v239, v106
	ds_read_b64_tr_b16 v[214:215], v190 offset:24704
	ds_read_b64_tr_b16 v[216:217], v190 offset:27264
	s_waitcnt lgkmcnt(6)
	v_mfma_f32_32x32x16_bf16 v[18:33], v[98:101], v[166:169], v[18:33]
	v_add_f32_e32 v238, v238, v107
	v_add_f32_e32 v239, v239, v108
	v_add_f32_e32 v238, v238, v109
	v_cvt_pk_bf16_f32 v106, v106, v107
	v_cvt_pk_bf16_f32 v107, v108, v109
	v_cvt_pk_bf16_f32 v108, v110, v111
	v_cvt_pk_bf16_f32 v109, v112, v113
	s_nop 0
	ds_read_b64_tr_b16 v[166:167], v190 offset:24768
	ds_read_b64_tr_b16 v[168:169], v190 offset:27328
	s_waitcnt lgkmcnt(6)
	v_mfma_f32_32x32x16_bf16 v[2:17], v[106:109], v[240:243], v[2:17]
	v_add_f32_e32 v239, v239, v110
	v_add_f32_e32 v238, v238, v111
	v_add_f32_e32 v239, v239, v112
	v_add_f32_e32 v238, v238, v113
	v_add_f32_e32 v239, v239, v238
	s_waitcnt lgkmcnt(4)
	v_mfma_f32_32x32x16_bf16 v[50:65], v[106:109], v[244:247], v[50:65]
	s_waitcnt lgkmcnt(2)
	v_mfma_f32_32x32x16_bf16 v[34:49], v[106:109], v[214:217], v[34:49]
	s_waitcnt lgkmcnt(0)
	v_mfma_f32_32x32x16_bf16 v[18:33], v[106:109], v[166:169], v[18:33]
	s_setprio 0
	s_movk_i32 s77, 0x110
	s_andn2_b64 vcc, exec, s[60:61]
	s_cbranch_vccnz .LBB0_47

.LBB0_59:
.LBB0_60:
	v_add3_u32 v153, s26, v178, v177
	ds_read_b64_tr_b16 v[154:155], v153 offset:9216
	ds_read_b64_tr_b16 v[156:157], v153 offset:11776
	ds_read_b64_tr_b16 v[190:191], v153 offset:9280
	ds_read_b64_tr_b16 v[192:193], v153 offset:11840
	ds_read_b64_tr_b16 v[214:215], v153 offset:9344
	ds_read_b64_tr_b16 v[216:217], v153 offset:11904
	ds_read_b64_tr_b16 v[234:235], v153 offset:9408
	ds_read_b64_tr_b16 v[236:237], v153 offset:11968
	ds_read_b64_tr_b16 v[240:241], v153 offset:14336
	ds_read_b64_tr_b16 v[242:243], v153 offset:16896
	ds_read_b64_tr_b16 v[244:245], v153 offset:14400
	ds_read_b64_tr_b16 v[246:247], v153 offset:16960
	ds_read_b64_tr_b16 v[206:207], v153 offset:14464
	ds_read_b64_tr_b16 v[208:209], v153 offset:17024
	ds_read_b64_tr_b16 v[166:167], v153 offset:14528
	ds_read_b64_tr_b16 v[168:169], v153 offset:17088
	v_exp_f32_e32 v82, v82
	v_exp_f32_e32 v83, v83
	v_exp_f32_e32 v84, v84
	v_exp_f32_e32 v85, v85
	v_exp_f32_e32 v86, v86
	v_exp_f32_e32 v87, v87
	v_exp_f32_e32 v88, v88
	v_exp_f32_e32 v89, v89
	v_add_f32_e32 v239, v82, v83
	v_add_f32_e32 v238, v238, v84
	v_add_f32_e32 v239, v239, v85
	v_cvt_pk_bf16_f32 v82, v82, v83
	v_cvt_pk_bf16_f32 v83, v84, v85
	v_cvt_pk_bf16_f32 v84, v86, v87
	v_cvt_pk_bf16_f32 v85, v88, v89
	s_setprio 1
	s_waitcnt lgkmcnt(14)
	v_mfma_f32_32x32x16_bf16 v[2:17], v[82:85], v[154:157], v[2:17]
	v_add_f32_e32 v238, v238, v86
	v_add_f32_e32 v239, v239, v87
	v_add_f32_e32 v238, v238, v88
	v_add_f32_e32 v239, v239, v89
	v_exp_f32_e32 v90, v90
	v_exp_f32_e32 v91, v91
	ds_read_b64_tr_b16 v[154:155], v153 offset:19456
	ds_read_b64_tr_b16 v[156:157], v153 offset:22016
	s_waitcnt lgkmcnt(14)
	v_mfma_f32_32x32x16_bf16 v[50:65], v[82:85], v[190:193], v[50:65]
	v_exp_f32_e32 v92, v92
	v_exp_f32_e32 v93, v93
	v_exp_f32_e32 v94, v94
	ds_read_b64_tr_b16 v[190:191], v153 offset:19520
	ds_read_b64_tr_b16 v[192:193], v153 offset:22080
	s_waitcnt lgkmcnt(14)
	v_mfma_f32_32x32x16_bf16 v[18:33], v[82:85], v[214:217], v[18:33]
	v_exp_f32_e32 v95, v95
	v_exp_f32_e32 v96, v96
	v_exp_f32_e32 v97, v97
	v_add_f32_e32 v238, v238, v90
	ds_read_b64_tr_b16 v[214:215], v153 offset:19584
	ds_read_b64_tr_b16 v[216:217], v153 offset:22144
	s_waitcnt lgkmcnt(14)
	v_mfma_f32_32x32x16_bf16 v[34:49], v[82:85], v[234:237], v[34:49]
	v_add_f32_e32 v239, v239, v91
	v_add_f32_e32 v238, v238, v92
	v_add_f32_e32 v239, v239, v93
	v_cvt_pk_bf16_f32 v90, v90, v91
	v_cvt_pk_bf16_f32 v91, v92, v93
	v_cvt_pk_bf16_f32 v92, v94, v95
	v_cvt_pk_bf16_f32 v93, v96, v97
	s_nop 0
	ds_read_b64_tr_b16 v[234:235], v153 offset:19648
	ds_read_b64_tr_b16 v[236:237], v153 offset:22208
	s_waitcnt lgkmcnt(14)
	v_mfma_f32_32x32x16_bf16 v[2:17], v[90:93], v[240:243], v[2:17]
	v_add_f32_e32 v238, v238, v94
	v_add_f32_e32 v239, v239, v95
	v_add_f32_e32 v238, v238, v96
	v_add_f32_e32 v239, v239, v97
	v_exp_f32_e32 v98, v98
	v_exp_f32_e32 v99, v99
	ds_read_b64_tr_b16 v[240:241], v153 offset:24576
	ds_read_b64_tr_b16 v[242:243], v153 offset:27136
	s_waitcnt lgkmcnt(14)
	v_mfma_f32_32x32x16_bf16 v[50:65], v[90:93], v[244:247], v[50:65]
	v_exp_f32_e32 v100, v100
	v_exp_f32_e32 v101, v101
	v_exp_f32_e32 v102, v102
	ds_read_b64_tr_b16 v[244:245], v153 offset:24640
	ds_read_b64_tr_b16 v[246:247], v153 offset:27200
	s_waitcnt lgkmcnt(14)
	v_mfma_f32_32x32x16_bf16 v[18:33], v[90:93], v[206:209], v[18:33]
	v_exp_f32_e32 v103, v103
	v_exp_f32_e32 v104, v104
	v_exp_f32_e32 v105, v105
	v_add_f32_e32 v238, v238, v98
	ds_read_b64_tr_b16 v[206:207], v153 offset:24704
	ds_read_b64_tr_b16 v[208:209], v153 offset:27264
	s_waitcnt lgkmcnt(14)
	v_mfma_f32_32x32x16_bf16 v[34:49], v[90:93], v[166:169], v[34:49]
	v_add_f32_e32 v239, v239, v99
	v_add_f32_e32 v238, v238, v100
	v_add_f32_e32 v239, v239, v101
	v_cvt_pk_bf16_f32 v98, v98, v99
	v_cvt_pk_bf16_f32 v99, v100, v101
	v_cvt_pk_bf16_f32 v100, v102, v103
	v_cvt_pk_bf16_f32 v101, v104, v105
	s_nop 0
	ds_read_b64_tr_b16 v[166:167], v153 offset:24768
	ds_read_b64_tr_b16 v[168:169], v153 offset:27328
	s_waitcnt lgkmcnt(14)
	v_mfma_f32_32x32x16_bf16 v[2:17], v[98:101], v[154:157], v[2:17]
	v_add_f32_e32 v238, v238, v102
	v_add_f32_e32 v239, v239, v103
	v_add_f32_e32 v238, v238, v104
	v_add_f32_e32 v239, v239, v105
	v_exp_f32_e32 v106, v106
	v_exp_f32_e32 v107, v107
	s_waitcnt lgkmcnt(12)
	v_mfma_f32_32x32x16_bf16 v[50:65], v[98:101], v[190:193], v[50:65]
	v_exp_f32_e32 v108, v108
	v_exp_f32_e32 v109, v109
	v_exp_f32_e32 v110, v110
	s_waitcnt lgkmcnt(10)
	v_mfma_f32_32x32x16_bf16 v[18:33], v[98:101], v[214:217], v[18:33]
	v_exp_f32_e32 v111, v111
	v_exp_f32_e32 v112, v112
	v_exp_f32_e32 v113, v113
	v_add_f32_e32 v238, v238, v106
	s_waitcnt lgkmcnt(8)
	v_mfma_f32_32x32x16_bf16 v[34:49], v[98:101], v[234:237], v[34:49]
	v_add_f32_e32 v239, v239, v107
	v_add_f32_e32 v238, v238, v108
	v_add_f32_e32 v239, v239, v109
	v_cvt_pk_bf16_f32 v106, v106, v107
	v_cvt_pk_bf16_f32 v107, v108, v109
	v_cvt_pk_bf16_f32 v108, v110, v111
	v_cvt_pk_bf16_f32 v109, v112, v113
	s_nop 0
	s_waitcnt lgkmcnt(6)
	v_mfma_f32_32x32x16_bf16 v[2:17], v[106:109], v[240:243], v[2:17]
	v_add_f32_e32 v238, v238, v110
	v_add_f32_e32 v239, v239, v111
	v_add_f32_e32 v238, v238, v112
	v_add_f32_e32 v239, v239, v113
	v_add_f32_e32 v238, v238, v239
	s_waitcnt lgkmcnt(4)
	v_mfma_f32_32x32x16_bf16 v[50:65], v[106:109], v[244:247], v[50:65]
	s_waitcnt lgkmcnt(2)
	v_mfma_f32_32x32x16_bf16 v[18:33], v[106:109], v[206:209], v[18:33]
	s_waitcnt lgkmcnt(0)
	v_mfma_f32_32x32x16_bf16 v[34:49], v[106:109], v[166:169], v[34:49]
	s_setprio 0
	s_movk_i32 s77, 0x110
	s_andn2_b64 vcc, exec, s[62:63]
	s_cbranch_vccnz .LBB0_62

.LBB0_74:
.LBB0_75:
	v_add3_u32 v190, s26, v182, v181
	ds_read_b64_tr_b16 v[214:215], v190 offset:9216
	ds_read_b64_tr_b16 v[216:217], v190 offset:11776
	ds_read_b64_tr_b16 v[244:245], v190 offset:9280
	ds_read_b64_tr_b16 v[246:247], v190 offset:11840
	ds_read_b64_tr_b16 v[206:207], v190 offset:9344
	ds_read_b64_tr_b16 v[208:209], v190 offset:11904
	ds_read_b64_tr_b16 v[166:167], v190 offset:9408
	ds_read_b64_tr_b16 v[168:169], v190 offset:11968
	v_exp_f32_e32 v82, v82
	v_exp_f32_e32 v83, v83
	v_exp_f32_e32 v84, v84
	v_exp_f32_e32 v85, v85
	v_exp_f32_e32 v86, v86
	v_exp_f32_e32 v87, v87
	v_exp_f32_e32 v88, v88
	v_exp_f32_e32 v89, v89
	v_add_f32_e32 v242, v82, v83
	v_add_f32_e32 v243, v243, v84
	v_add_f32_e32 v242, v242, v85
	v_cvt_pk_bf16_f32 v82, v82, v83
	v_cvt_pk_bf16_f32 v83, v84, v85
	v_cvt_pk_bf16_f32 v84, v86, v87
	v_cvt_pk_bf16_f32 v85, v88, v89
	s_setprio 1
	s_waitcnt lgkmcnt(6)
	v_mfma_f32_32x32x16_bf16 v[2:17], v[82:85], v[214:217], v[2:17]
	v_add_f32_e32 v243, v243, v86
	v_add_f32_e32 v242, v242, v87
	v_add_f32_e32 v243, v243, v88
	v_add_f32_e32 v242, v242, v89
	v_exp_f32_e32 v90, v90
	v_exp_f32_e32 v91, v91
	ds_read_b64_tr_b16 v[214:215], v190 offset:14336
	ds_read_b64_tr_b16 v[216:217], v190 offset:16896
	s_waitcnt lgkmcnt(6)
	v_mfma_f32_32x32x16_bf16 v[50:65], v[82:85], v[244:247], v[50:65]
	v_exp_f32_e32 v92, v92
	v_exp_f32_e32 v93, v93
	v_exp_f32_e32 v94, v94
	ds_read_b64_tr_b16 v[244:245], v190 offset:14400
	ds_read_b64_tr_b16 v[246:247], v190 offset:16960
	s_waitcnt lgkmcnt(6)
	v_mfma_f32_32x32x16_bf16 v[34:49], v[82:85], v[206:209], v[34:49]
	v_exp_f32_e32 v95, v95
	v_exp_f32_e32 v96, v96
	v_exp_f32_e32 v97, v97
	v_add_f32_e32 v243, v243, v90
	ds_read_b64_tr_b16 v[206:207], v190 offset:14464
	ds_read_b64_tr_b16 v[208:209], v190 offset:17024
	s_waitcnt lgkmcnt(6)
	v_mfma_f32_32x32x16_bf16 v[18:33], v[82:85], v[166:169], v[18:33]
	v_add_f32_e32 v242, v242, v91
	v_add_f32_e32 v243, v243, v92
	v_add_f32_e32 v242, v242, v93
	v_cvt_pk_bf16_f32 v90, v90, v91
	v_cvt_pk_bf16_f32 v91, v92, v93
	v_cvt_pk_bf16_f32 v92, v94, v95
	v_cvt_pk_bf16_f32 v93, v96, v97
	s_nop 0
	ds_read_b64_tr_b16 v[166:167], v190 offset:14528
	ds_read_b64_tr_b16 v[168:169], v190 offset:17088
	s_waitcnt lgkmcnt(6)
	v_mfma_f32_32x32x16_bf16 v[2:17], v[90:93], v[214:217], v[2:17]
	v_add_f32_e32 v243, v243, v94
	v_add_f32_e32 v242, v242, v95
	v_add_f32_e32 v243, v243, v96
	v_add_f32_e32 v242, v242, v97
	v_exp_f32_e32 v98, v98
	v_exp_f32_e32 v99, v99
	ds_read_b64_tr_b16 v[214:215], v190 offset:19456
	ds_read_b64_tr_b16 v[216:217], v190 offset:22016
	s_waitcnt lgkmcnt(6)
	v_mfma_f32_32x32x16_bf16 v[50:65], v[90:93], v[244:247], v[50:65]
	v_exp_f32_e32 v100, v100
	v_exp_f32_e32 v101, v101
	v_exp_f32_e32 v102, v102
	ds_read_b64_tr_b16 v[244:245], v190 offset:19520
	ds_read_b64_tr_b16 v[246:247], v190 offset:22080
	s_waitcnt lgkmcnt(6)
	v_mfma_f32_32x32x16_bf16 v[34:49], v[90:93], v[206:209], v[34:49]
	v_exp_f32_e32 v103, v103
	v_exp_f32_e32 v104, v104
	v_exp_f32_e32 v105, v105
	v_add_f32_e32 v243, v243, v98
	ds_read_b64_tr_b16 v[206:207], v190 offset:19584
	ds_read_b64_tr_b16 v[208:209], v190 offset:22144
	s_waitcnt lgkmcnt(6)
	v_mfma_f32_32x32x16_bf16 v[18:33], v[90:93], v[166:169], v[18:33]
	v_add_f32_e32 v242, v242, v99
	v_add_f32_e32 v243, v243, v100
	v_add_f32_e32 v242, v242, v101
	v_cvt_pk_bf16_f32 v98, v98, v99
	v_cvt_pk_bf16_f32 v99, v100, v101
	v_cvt_pk_bf16_f32 v100, v102, v103
	v_cvt_pk_bf16_f32 v101, v104, v105
	s_nop 0
	ds_read_b64_tr_b16 v[166:167], v190 offset:19648
	ds_read_b64_tr_b16 v[168:169], v190 offset:22208
	s_waitcnt lgkmcnt(6)
	v_mfma_f32_32x32x16_bf16 v[2:17], v[98:101], v[214:217], v[2:17]
	v_add_f32_e32 v243, v243, v102
	v_add_f32_e32 v242, v242, v103
	v_add_f32_e32 v243, v243, v104
	v_add_f32_e32 v242, v242, v105
	v_exp_f32_e32 v106, v106
	v_exp_f32_e32 v107, v107
	ds_read_b64_tr_b16 v[214:215], v190 offset:24576
	ds_read_b64_tr_b16 v[216:217], v190 offset:27136
	s_waitcnt lgkmcnt(6)
	v_mfma_f32_32x32x16_bf16 v[50:65], v[98:101], v[244:247], v[50:65]
	v_exp_f32_e32 v108, v108
	v_exp_f32_e32 v109, v109
	v_exp_f32_e32 v110, v110
	ds_read_b64_tr_b16 v[244:245], v190 offset:24640
	ds_read_b64_tr_b16 v[246:247], v190 offset:27200
	s_waitcnt lgkmcnt(6)
	v_mfma_f32_32x32x16_bf16 v[34:49], v[98:101], v[206:209], v[34:49]
	v_exp_f32_e32 v111, v111
	v_exp_f32_e32 v112, v112
	v_exp_f32_e32 v113, v113
	v_add_f32_e32 v243, v243, v106
	ds_read_b64_tr_b16 v[206:207], v190 offset:24704
	ds_read_b64_tr_b16 v[208:209], v190 offset:27264
	s_waitcnt lgkmcnt(6)
	v_mfma_f32_32x32x16_bf16 v[18:33], v[98:101], v[166:169], v[18:33]
	v_add_f32_e32 v242, v242, v107
	v_add_f32_e32 v243, v243, v108
	v_add_f32_e32 v242, v242, v109
	v_cvt_pk_bf16_f32 v106, v106, v107
	v_cvt_pk_bf16_f32 v107, v108, v109
	v_cvt_pk_bf16_f32 v108, v110, v111
	v_cvt_pk_bf16_f32 v109, v112, v113
	s_nop 0
	ds_read_b64_tr_b16 v[166:167], v190 offset:24768
	ds_read_b64_tr_b16 v[168:169], v190 offset:27328
	s_waitcnt lgkmcnt(6)
	v_mfma_f32_32x32x16_bf16 v[2:17], v[106:109], v[214:217], v[2:17]
	v_add_f32_e32 v243, v243, v110
	v_add_f32_e32 v242, v242, v111
	v_add_f32_e32 v243, v243, v112
	v_add_f32_e32 v242, v242, v113
	v_add_f32_e32 v243, v243, v242
	s_waitcnt lgkmcnt(4)
	v_mfma_f32_32x32x16_bf16 v[50:65], v[106:109], v[244:247], v[50:65]
	s_waitcnt lgkmcnt(2)
	v_mfma_f32_32x32x16_bf16 v[34:49], v[106:109], v[206:209], v[34:49]
	s_waitcnt lgkmcnt(0)
	v_mfma_f32_32x32x16_bf16 v[18:33], v[106:109], v[166:169], v[18:33]
	s_setprio 0
	s_movk_i32 s77, 0x110
	s_andn2_b64 vcc, exec, s[28:29]
	s_cbranch_vccnz .LBB0_77

.LBB0_89:
.LBB0_90:
	v_add3_u32 v153, s26, v182, v181
	ds_read_b64_tr_b16 v[154:155], v153 offset:9216
	ds_read_b64_tr_b16 v[156:157], v153 offset:11776
	ds_read_b64_tr_b16 v[162:163], v153 offset:9280
	ds_read_b64_tr_b16 v[164:165], v153 offset:11840
	ds_read_b64_tr_b16 v[190:191], v153 offset:9344
	ds_read_b64_tr_b16 v[192:193], v153 offset:11904
	ds_read_b64_tr_b16 v[206:207], v153 offset:9408
	ds_read_b64_tr_b16 v[208:209], v153 offset:11968
	ds_read_b64_tr_b16 v[166:167], v153 offset:14336
	ds_read_b64_tr_b16 v[168:169], v153 offset:16896
	ds_read_b64_tr_b16 v[214:215], v153 offset:14400
	ds_read_b64_tr_b16 v[216:217], v153 offset:16960
	ds_read_b64_tr_b16 v[240:241], v153 offset:14464
	ds_read_b64_tr_b16 v[242:243], v153 offset:17024
	ds_read_b64_tr_b16 v[244:245], v153 offset:14528
	ds_read_b64_tr_b16 v[246:247], v153 offset:17088
	v_exp_f32_e32 v82, v82
	v_exp_f32_e32 v83, v83
	v_exp_f32_e32 v84, v84
	v_exp_f32_e32 v85, v85
	v_exp_f32_e32 v86, v86
	v_exp_f32_e32 v87, v87
	v_exp_f32_e32 v88, v88
	v_exp_f32_e32 v89, v89
	v_add_f32_e32 v239, v82, v83
	v_add_f32_e32 v238, v238, v84
	v_add_f32_e32 v239, v239, v85
	v_cvt_pk_bf16_f32 v82, v82, v83
	v_cvt_pk_bf16_f32 v83, v84, v85
	v_cvt_pk_bf16_f32 v84, v86, v87
	v_cvt_pk_bf16_f32 v85, v88, v89
	s_setprio 1
	s_waitcnt lgkmcnt(14)
	v_mfma_f32_32x32x16_bf16 v[2:17], v[82:85], v[154:157], v[2:17]
	v_add_f32_e32 v238, v238, v86
	v_add_f32_e32 v239, v239, v87
	v_add_f32_e32 v238, v238, v88
	v_add_f32_e32 v239, v239, v89
	v_exp_f32_e32 v90, v90
	v_exp_f32_e32 v91, v91
	ds_read_b64_tr_b16 v[154:155], v153 offset:19456
	ds_read_b64_tr_b16 v[156:157], v153 offset:22016
	s_waitcnt lgkmcnt(14)
	v_mfma_f32_32x32x16_bf16 v[50:65], v[82:85], v[162:165], v[50:65]
	v_exp_f32_e32 v92, v92
	v_exp_f32_e32 v93, v93
	v_exp_f32_e32 v94, v94
	ds_read_b64_tr_b16 v[162:163], v153 offset:19520
	ds_read_b64_tr_b16 v[164:165], v153 offset:22080
	s_waitcnt lgkmcnt(14)
	v_mfma_f32_32x32x16_bf16 v[18:33], v[82:85], v[190:193], v[18:33]
	v_exp_f32_e32 v95, v95
	v_exp_f32_e32 v96, v96
	v_exp_f32_e32 v97, v97
	v_add_f32_e32 v238, v238, v90
	ds_read_b64_tr_b16 v[190:191], v153 offset:19584
	ds_read_b64_tr_b16 v[192:193], v153 offset:22144
	s_waitcnt lgkmcnt(14)
	v_mfma_f32_32x32x16_bf16 v[34:49], v[82:85], v[206:209], v[34:49]
	v_add_f32_e32 v239, v239, v91
	v_add_f32_e32 v238, v238, v92
	v_add_f32_e32 v239, v239, v93
	v_cvt_pk_bf16_f32 v90, v90, v91
	v_cvt_pk_bf16_f32 v91, v92, v93
	v_cvt_pk_bf16_f32 v92, v94, v95
	v_cvt_pk_bf16_f32 v93, v96, v97
	s_nop 0
	ds_read_b64_tr_b16 v[206:207], v153 offset:19648
	ds_read_b64_tr_b16 v[208:209], v153 offset:22208
	s_waitcnt lgkmcnt(14)
	v_mfma_f32_32x32x16_bf16 v[2:17], v[90:93], v[166:169], v[2:17]
	v_add_f32_e32 v238, v238, v94
	v_add_f32_e32 v239, v239, v95
	v_add_f32_e32 v238, v238, v96
	v_add_f32_e32 v239, v239, v97
	v_exp_f32_e32 v98, v98
	v_exp_f32_e32 v99, v99
	ds_read_b64_tr_b16 v[166:167], v153 offset:24576
	ds_read_b64_tr_b16 v[168:169], v153 offset:27136
	s_waitcnt lgkmcnt(14)
	v_mfma_f32_32x32x16_bf16 v[50:65], v[90:93], v[214:217], v[50:65]
	v_exp_f32_e32 v100, v100
	v_exp_f32_e32 v101, v101
	v_exp_f32_e32 v102, v102
	ds_read_b64_tr_b16 v[214:215], v153 offset:24640
	ds_read_b64_tr_b16 v[216:217], v153 offset:27200
	s_waitcnt lgkmcnt(14)
	v_mfma_f32_32x32x16_bf16 v[18:33], v[90:93], v[240:243], v[18:33]
	v_exp_f32_e32 v103, v103
	v_exp_f32_e32 v104, v104
	v_exp_f32_e32 v105, v105
	v_add_f32_e32 v238, v238, v98
	ds_read_b64_tr_b16 v[240:241], v153 offset:24704
	ds_read_b64_tr_b16 v[242:243], v153 offset:27264
	s_waitcnt lgkmcnt(14)
	v_mfma_f32_32x32x16_bf16 v[34:49], v[90:93], v[244:247], v[34:49]
	v_add_f32_e32 v239, v239, v99
	v_add_f32_e32 v238, v238, v100
	v_add_f32_e32 v239, v239, v101
	v_cvt_pk_bf16_f32 v98, v98, v99
	v_cvt_pk_bf16_f32 v99, v100, v101
	v_cvt_pk_bf16_f32 v100, v102, v103
	v_cvt_pk_bf16_f32 v101, v104, v105
	s_nop 0
	ds_read_b64_tr_b16 v[244:245], v153 offset:24768
	ds_read_b64_tr_b16 v[246:247], v153 offset:27328
	s_waitcnt lgkmcnt(14)
	v_mfma_f32_32x32x16_bf16 v[2:17], v[98:101], v[154:157], v[2:17]
	v_add_f32_e32 v238, v238, v102
	v_add_f32_e32 v239, v239, v103
	v_add_f32_e32 v238, v238, v104
	v_add_f32_e32 v239, v239, v105
	v_exp_f32_e32 v106, v106
	v_exp_f32_e32 v107, v107
	s_waitcnt lgkmcnt(12)
	v_mfma_f32_32x32x16_bf16 v[50:65], v[98:101], v[162:165], v[50:65]
	v_exp_f32_e32 v108, v108
	v_exp_f32_e32 v109, v109
	v_exp_f32_e32 v110, v110
	s_waitcnt lgkmcnt(10)
	v_mfma_f32_32x32x16_bf16 v[18:33], v[98:101], v[190:193], v[18:33]
	v_exp_f32_e32 v111, v111
	v_exp_f32_e32 v112, v112
	v_exp_f32_e32 v113, v113
	v_add_f32_e32 v238, v238, v106
	s_waitcnt lgkmcnt(8)
	v_mfma_f32_32x32x16_bf16 v[34:49], v[98:101], v[206:209], v[34:49]
	v_add_f32_e32 v239, v239, v107
	v_add_f32_e32 v238, v238, v108
	v_add_f32_e32 v239, v239, v109
	v_cvt_pk_bf16_f32 v106, v106, v107
	v_cvt_pk_bf16_f32 v107, v108, v109
	v_cvt_pk_bf16_f32 v108, v110, v111
	v_cvt_pk_bf16_f32 v109, v112, v113
	s_nop 0
	s_waitcnt lgkmcnt(6)
	v_mfma_f32_32x32x16_bf16 v[2:17], v[106:109], v[166:169], v[2:17]
	v_add_f32_e32 v238, v238, v110
	v_add_f32_e32 v239, v239, v111
	v_add_f32_e32 v238, v238, v112
	v_add_f32_e32 v239, v239, v113
	v_add_f32_e32 v238, v238, v239
	s_waitcnt lgkmcnt(4)
	v_mfma_f32_32x32x16_bf16 v[50:65], v[106:109], v[214:217], v[50:65]
	s_waitcnt lgkmcnt(2)
	v_mfma_f32_32x32x16_bf16 v[18:33], v[106:109], v[240:243], v[18:33]
	s_waitcnt lgkmcnt(0)
	v_mfma_f32_32x32x16_bf16 v[34:49], v[106:109], v[244:247], v[34:49]
	s_setprio 0
	s_movk_i32 s77, 0x110
	s_andn2_b64 vcc, exec, s[28:29]
	s_cbranch_vccnz .LBB0_92
